# P0 bias1 dot products (one output per wave on 64 workgroups): 32-trip load/vmcnt(0)/fmac loop replaced by 64 loads issued up front and 32 fmacs in the same order behind counted waits
# baseline (speedup 1.0000x reference)
.LBB0_84:
	global_load_dword v192, v[12:13], off
	global_load_dword v148, v[14:15], off
	v_lshl_add_u64 v[12:13], v[12:13], 0, s[14:15]
	v_lshl_add_u64 v[14:15], v[14:15], 0, s[16:17]
	global_load_dword v193, v[12:13], off
	global_load_dword v149, v[14:15], off
	v_lshl_add_u64 v[12:13], v[12:13], 0, s[14:15]
	v_lshl_add_u64 v[14:15], v[14:15], 0, s[16:17]
	global_load_dword v194, v[12:13], off
	global_load_dword v150, v[14:15], off
	v_lshl_add_u64 v[12:13], v[12:13], 0, s[14:15]
	v_lshl_add_u64 v[14:15], v[14:15], 0, s[16:17]
	global_load_dword v195, v[12:13], off
	global_load_dword v151, v[14:15], off
	v_lshl_add_u64 v[12:13], v[12:13], 0, s[14:15]
	v_lshl_add_u64 v[14:15], v[14:15], 0, s[16:17]
	global_load_dword v196, v[12:13], off
	global_load_dword v152, v[14:15], off
	v_lshl_add_u64 v[12:13], v[12:13], 0, s[14:15]
	v_lshl_add_u64 v[14:15], v[14:15], 0, s[16:17]
	global_load_dword v197, v[12:13], off
	global_load_dword v153, v[14:15], off
	v_lshl_add_u64 v[12:13], v[12:13], 0, s[14:15]
	v_lshl_add_u64 v[14:15], v[14:15], 0, s[16:17]
	global_load_dword v198, v[12:13], off
	global_load_dword v154, v[14:15], off
	v_lshl_add_u64 v[12:13], v[12:13], 0, s[14:15]
	v_lshl_add_u64 v[14:15], v[14:15], 0, s[16:17]
	global_load_dword v199, v[12:13], off
	global_load_dword v155, v[14:15], off
	v_lshl_add_u64 v[12:13], v[12:13], 0, s[14:15]
	v_lshl_add_u64 v[14:15], v[14:15], 0, s[16:17]
	global_load_dword v200, v[12:13], off
	global_load_dword v156, v[14:15], off
	v_lshl_add_u64 v[12:13], v[12:13], 0, s[14:15]
	v_lshl_add_u64 v[14:15], v[14:15], 0, s[16:17]
	global_load_dword v201, v[12:13], off
	global_load_dword v157, v[14:15], off
	v_lshl_add_u64 v[12:13], v[12:13], 0, s[14:15]
	v_lshl_add_u64 v[14:15], v[14:15], 0, s[16:17]
	global_load_dword v202, v[12:13], off
	global_load_dword v158, v[14:15], off
	v_lshl_add_u64 v[12:13], v[12:13], 0, s[14:15]
	v_lshl_add_u64 v[14:15], v[14:15], 0, s[16:17]
	global_load_dword v203, v[12:13], off
	global_load_dword v159, v[14:15], off
	v_lshl_add_u64 v[12:13], v[12:13], 0, s[14:15]
	v_lshl_add_u64 v[14:15], v[14:15], 0, s[16:17]
	global_load_dword v204, v[12:13], off
	global_load_dword v160, v[14:15], off
	v_lshl_add_u64 v[12:13], v[12:13], 0, s[14:15]
	v_lshl_add_u64 v[14:15], v[14:15], 0, s[16:17]
	global_load_dword v205, v[12:13], off
	global_load_dword v161, v[14:15], off
	v_lshl_add_u64 v[12:13], v[12:13], 0, s[14:15]
	v_lshl_add_u64 v[14:15], v[14:15], 0, s[16:17]
	global_load_dword v206, v[12:13], off
	global_load_dword v162, v[14:15], off
	v_lshl_add_u64 v[12:13], v[12:13], 0, s[14:15]
	v_lshl_add_u64 v[14:15], v[14:15], 0, s[16:17]
	global_load_dword v207, v[12:13], off
	global_load_dword v163, v[14:15], off
	v_lshl_add_u64 v[12:13], v[12:13], 0, s[14:15]
	v_lshl_add_u64 v[14:15], v[14:15], 0, s[16:17]
	global_load_dword v208, v[12:13], off
	global_load_dword v164, v[14:15], off
	v_lshl_add_u64 v[12:13], v[12:13], 0, s[14:15]
	v_lshl_add_u64 v[14:15], v[14:15], 0, s[16:17]
	global_load_dword v209, v[12:13], off
	global_load_dword v165, v[14:15], off
	v_lshl_add_u64 v[12:13], v[12:13], 0, s[14:15]
	v_lshl_add_u64 v[14:15], v[14:15], 0, s[16:17]
	global_load_dword v210, v[12:13], off
	global_load_dword v166, v[14:15], off
	v_lshl_add_u64 v[12:13], v[12:13], 0, s[14:15]
	v_lshl_add_u64 v[14:15], v[14:15], 0, s[16:17]
	global_load_dword v211, v[12:13], off
	global_load_dword v167, v[14:15], off
	v_lshl_add_u64 v[12:13], v[12:13], 0, s[14:15]
	v_lshl_add_u64 v[14:15], v[14:15], 0, s[16:17]
	global_load_dword v212, v[12:13], off
	global_load_dword v168, v[14:15], off
	v_lshl_add_u64 v[12:13], v[12:13], 0, s[14:15]
	v_lshl_add_u64 v[14:15], v[14:15], 0, s[16:17]
	global_load_dword v213, v[12:13], off
	global_load_dword v169, v[14:15], off
	v_lshl_add_u64 v[12:13], v[12:13], 0, s[14:15]
	v_lshl_add_u64 v[14:15], v[14:15], 0, s[16:17]
	global_load_dword v214, v[12:13], off
	global_load_dword v170, v[14:15], off
	v_lshl_add_u64 v[12:13], v[12:13], 0, s[14:15]
	v_lshl_add_u64 v[14:15], v[14:15], 0, s[16:17]
	global_load_dword v215, v[12:13], off
	global_load_dword v171, v[14:15], off
	v_lshl_add_u64 v[12:13], v[12:13], 0, s[14:15]
	v_lshl_add_u64 v[14:15], v[14:15], 0, s[16:17]
	global_load_dword v216, v[12:13], off
	global_load_dword v172, v[14:15], off
	v_lshl_add_u64 v[12:13], v[12:13], 0, s[14:15]
	v_lshl_add_u64 v[14:15], v[14:15], 0, s[16:17]
	global_load_dword v217, v[12:13], off
	global_load_dword v173, v[14:15], off
	v_lshl_add_u64 v[12:13], v[12:13], 0, s[14:15]
	v_lshl_add_u64 v[14:15], v[14:15], 0, s[16:17]
	global_load_dword v218, v[12:13], off
	global_load_dword v174, v[14:15], off
	v_lshl_add_u64 v[12:13], v[12:13], 0, s[14:15]
	v_lshl_add_u64 v[14:15], v[14:15], 0, s[16:17]
	global_load_dword v219, v[12:13], off
	global_load_dword v175, v[14:15], off
	v_lshl_add_u64 v[12:13], v[12:13], 0, s[14:15]
	v_lshl_add_u64 v[14:15], v[14:15], 0, s[16:17]
	global_load_dword v220, v[12:13], off
	global_load_dword v176, v[14:15], off
	v_lshl_add_u64 v[12:13], v[12:13], 0, s[14:15]
	v_lshl_add_u64 v[14:15], v[14:15], 0, s[16:17]
	global_load_dword v221, v[12:13], off
	global_load_dword v177, v[14:15], off
	v_lshl_add_u64 v[12:13], v[12:13], 0, s[14:15]
	v_lshl_add_u64 v[14:15], v[14:15], 0, s[16:17]
	global_load_dword v222, v[12:13], off
	global_load_dword v179, v[14:15], off
	v_lshl_add_u64 v[12:13], v[12:13], 0, s[14:15]
	v_lshl_add_u64 v[14:15], v[14:15], 0, s[16:17]
	global_load_dword v223, v[12:13], off
	global_load_dword v180, v[14:15], off
	s_waitcnt vmcnt(62)
	v_fmac_f32_e32 v6, v192, v148
	s_waitcnt vmcnt(60)
	v_fmac_f32_e32 v6, v193, v149
	s_waitcnt vmcnt(58)
	v_fmac_f32_e32 v6, v194, v150
	s_waitcnt vmcnt(56)
	v_fmac_f32_e32 v6, v195, v151
	s_waitcnt vmcnt(54)
	v_fmac_f32_e32 v6, v196, v152
	s_waitcnt vmcnt(52)
	v_fmac_f32_e32 v6, v197, v153
	s_waitcnt vmcnt(50)
	v_fmac_f32_e32 v6, v198, v154
	s_waitcnt vmcnt(48)
	v_fmac_f32_e32 v6, v199, v155
	s_waitcnt vmcnt(46)
	v_fmac_f32_e32 v6, v200, v156
	s_waitcnt vmcnt(44)
	v_fmac_f32_e32 v6, v201, v157
	s_waitcnt vmcnt(42)
	v_fmac_f32_e32 v6, v202, v158
	s_waitcnt vmcnt(40)
	v_fmac_f32_e32 v6, v203, v159
	s_waitcnt vmcnt(38)
	v_fmac_f32_e32 v6, v204, v160
	s_waitcnt vmcnt(36)
	v_fmac_f32_e32 v6, v205, v161
	s_waitcnt vmcnt(34)
	v_fmac_f32_e32 v6, v206, v162
	s_waitcnt vmcnt(32)
	v_fmac_f32_e32 v6, v207, v163
	s_waitcnt vmcnt(30)
	v_fmac_f32_e32 v6, v208, v164
	s_waitcnt vmcnt(28)
	v_fmac_f32_e32 v6, v209, v165
	s_waitcnt vmcnt(26)
	v_fmac_f32_e32 v6, v210, v166
	s_waitcnt vmcnt(24)
	v_fmac_f32_e32 v6, v211, v167
	s_waitcnt vmcnt(22)
	v_fmac_f32_e32 v6, v212, v168
	s_waitcnt vmcnt(20)
	v_fmac_f32_e32 v6, v213, v169
	s_waitcnt vmcnt(18)
	v_fmac_f32_e32 v6, v214, v170
	s_waitcnt vmcnt(16)
	v_fmac_f32_e32 v6, v215, v171
	s_waitcnt vmcnt(14)
	v_fmac_f32_e32 v6, v216, v172
	s_waitcnt vmcnt(12)
	v_fmac_f32_e32 v6, v217, v173
	s_waitcnt vmcnt(10)
	v_fmac_f32_e32 v6, v218, v174
	s_waitcnt vmcnt(8)
	v_fmac_f32_e32 v6, v219, v175
	s_waitcnt vmcnt(6)
	v_fmac_f32_e32 v6, v220, v176
	s_waitcnt vmcnt(4)
	v_fmac_f32_e32 v6, v221, v177
	s_waitcnt vmcnt(2)
	v_fmac_f32_e32 v6, v222, v179
	s_waitcnt vmcnt(0)
	v_fmac_f32_e32 v6, v223, v180
	s_or_b64 exec, exec, s[18:19]
	ds_bpermute_b32 v11, v1, v6
	s_waitcnt lgkmcnt(0)
	v_add_f32_e32 v6, v6, v11
	ds_bpermute_b32 v11, v3, v6
	s_waitcnt lgkmcnt(0)
	v_add_f32_e32 v6, v6, v11
	ds_bpermute_b32 v11, v16, v6
	s_waitcnt lgkmcnt(0)
	v_add_f32_e32 v6, v6, v11
	ds_bpermute_b32 v11, v17, v6
	s_waitcnt lgkmcnt(0)
	v_add_f32_e32 v6, v6, v11
	ds_bpermute_b32 v11, v19, v6
	s_waitcnt lgkmcnt(0)
	v_add_f32_e32 v6, v6, v11
	ds_bpermute_b32 v12, v21, v6
	s_and_saveexec_b64 s[0:1], vcc
	s_cbranch_execz .LBB0_82
	v_ashrrev_i32_e32 v11, 31, v10
	v_lshl_add_u64 v[14:15], v[10:11], 2, s[12:13]
	s_waitcnt lgkmcnt(0)
	v_add_f32_e32 v6, v6, v12
	global_store_dword v[14:15], v6, off
	s_branch .LBB0_82
